# mLSTM unit: first K/V tile requested with the Q fragments at the top of the unit (was after the block-state phase)
# speedup vs baseline: 1.0058x; 1.0039x over previous
; #define LAS __attribute__((address_space(3)))
; DI void mlstm_unit(const Args& a, LAS unsigned char* lds, int b, int h, int J) {
;     ...
;     const int tid = tid_, lane = tid & 63, wave = __builtin_amdgcn_readfirstlane(tid >> 6), r = lane & 31, h2 = lane >> 5;
;     const int seq = b * 4 + h, t = 256 * J + 32 * wave + r; const size_t row = (size_t)b * T + t;
;     const bf16_t* QB = (const bf16_t*)(ws + WS_QB); const bf16_t* KB = (const bf16_t*)(ws + WS_KB) + (size_t)b * T * 512 + h * 128; const bf16_t* VB = (const bf16_t*)(ws + WS_VB) + (size_t)b * T * 512 + h * 128;
;     const float* BETA = (const float*)(ws + WS_BETA) + seq * 2048; const float* ALPHA = (const float*)(ws + WS_ALPHA) + seq * 2048; const float* MTG = (const float*)(ws + WS_MT) + seq * 2048;
;     const LAS unsigned char* Ks = lds + A_KS; const LAS unsigned char* Vs = lds + A_VS; LAS float* BS = (LAS float*)(lds + M_BS); LAS float* KAP = (LAS float*)(lds + M_KAP); LAS float* NV = (LAS float*)(lds + M_NV);
;     bf16x8 qf[8];
; #pragma unroll
;     for (int ks = 0; ks < 8; ++ks) qf[ks] = *(const bf16x8*)(QB + row * 512 + h * 128 + 16 * ks + 8 * h2);
;     const float aln = ALPHA[t], al = aln * LOG2E, mt = MTG[t];
;     ...
;     if (J > 0) {
;         const int e1 = 256 * J - 1;
;         if (tid < J) { const int ep = 256 * tid + 255; const float Be1 = ALPHA[e1] + MTG[e1], Bep = ALPHA[ep] + MTG[ep];
;             KAP[tid] = __expf((Be1 - Bep) + ((const float*)(ws + WS_MU))[seq * 8 + tid] - MTG[e1]); }
;     ...
;     for (int i = 0; i < 2; ++i) { const int idx = tid + 512 * i, rw = 64 * kt0 + (idx >> 4), ch = idx & 15; kreg[i] = *(const u32x4*)(KB + (size_t)rw * 512 + ch * 8); vreg[i] = *(const u32x4*)(VB + (size_t)rw * 512 + ch * 8); }
.LBB0_2094:
	s_add_i32 s0, s20, 0xfffffda0
	s_ashr_i32 s1, s0, 31
	s_lshr_b32 s1, s1, 24
	s_add_i32 s1, s0, s1
	s_and_b32 s1, s1, 0xffffff00
	s_sub_i32 s49, s0, s1
	v_mov_b32_e32 v74, v0
	s_ashr_i32 s50, s49, 5
	s_sub_i32 s51, 7, s50
	v_readfirstlane_b32 s52, v74
	s_ashr_i32 s0, s52, 1
	s_lshl_b32 s18, s51, 8
	s_andn2_b32 s0, s0, 31
	v_and_b32_e32 v76, 31, v74
	s_add_i32 s0, s18, s0
	v_or_b32_e32 v156, s0, v76
	s_lshl_b32 s0, s49, 9
	s_and_b32 s10, s0, 0x3800
	v_ashrrev_i32_e32 v157, 31, v156
	v_lshl_add_u64 v[152:153], v[156:157], 0, s[10:11]
	s_lshl_b32 s0, s49, 7
	s_and_b32 s48, s0, 0x180
	v_lshlrev_b64 v[154:155], 10, v[152:153]
	v_bfe_u32 v75, v74, 5, 1
	v_lshl_add_u64 v[4:5], s[4:5], 0, v[154:155]
	s_lshl_b32 s16, s48, 1
	s_mov_b32 s17, s11
	v_lshl_add_u64 v[4:5], v[4:5], 0, s[16:17]
	v_lshlrev_b32_e32 v2, 4, v75
	v_lshl_add_u64 v[4:5], v[4:5], 0, v[2:3]
	s_and_b32 s53, s49, 31
	global_load_dwordx4 v[100:103], v[4:5], off
	global_load_dwordx4 v[104:107], v[4:5], off offset:32
	global_load_dwordx4 v[108:111], v[4:5], off offset:64
	global_load_dwordx4 v[112:115], v[4:5], off offset:96
	global_load_dwordx4 v[116:119], v[4:5], off offset:128
	global_load_dwordx4 v[120:123], v[4:5], off offset:160
	global_load_dwordx4 v[124:127], v[4:5], off offset:192
	global_load_dwordx4 v[128:131], v[4:5], off offset:224
	s_lshl_b32 s2, s53, 13
	s_add_u32 s0, s26, s2
	s_addc_u32 s1, s27, 0
	s_add_u32 s2, s28, s2
	v_lshlrev_b64 v[4:5], 2, v[156:157]
	s_addc_u32 s3, s29, 0
	v_lshl_add_u64 v[6:7], s[0:1], 0, v[4:5]
	v_lshl_add_u64 v[4:5], s[2:3], 0, v[4:5]
	global_load_dword v77, v[6:7], off
	global_load_dword v157, v[4:5], off
	s_lshl_b32 s70, s10, 10
	s_add_u32 s66, s24, s70
	s_addc_u32 s67, s25, 0
	s_add_u32 s66, s66, s16
	s_addc_u32 s67, s67, 0
	s_add_u32 s68, s30, s70
	s_addc_u32 s69, s31, 0
	s_add_u32 s68, s68, s16
	s_addc_u32 s69, s69, 0
	v_ashrrev_i32_e32 v228, 4, v74
	v_lshlrev_b32_e32 v230, 4, v74
	v_add_u32_e32 v232, s18, v228
	v_and_b32_e32 v230, 0xf0, v230
	v_mov_b32_e32 v231, 0
	v_ashrrev_i32_e32 v233, 31, v232
	v_lshl_add_u64 v[236:237], s[68:69], 0, v[230:231]
	v_lshl_add_u64 v[238:239], s[66:67], 0, v[230:231]
	v_lshlrev_b64 v[232:233], 10, v[232:233]
	v_lshl_add_u64 v[240:241], v[236:237], 0, v[232:233]
	v_lshl_add_u64 v[232:233], v[238:239], 0, v[232:233]
	global_load_dwordx4 v[200:203], v[240:241], off
	global_load_dwordx4 v[204:207], v[232:233], off
	v_add_u32_e32 v230, 0x200, v74
	v_ashrrev_i32_e32 v230, 4, v230
	v_add_u32_e32 v240, s18, v230
	v_ashrrev_i32_e32 v241, 31, v240
	v_lshlrev_b64 v[240:241], 10, v[240:241]
	v_lshl_add_u64 v[236:237], v[236:237], 0, v[240:241]
	v_lshl_add_u64 v[238:239], v[238:239], 0, v[240:241]
	global_load_dwordx4 v[208:211], v[236:237], off
	global_load_dwordx4 v[212:215], v[238:239], off
	s_cmp_lg_u32 s50, 7
	s_mov_b64 s[20:21], -1
	s_barrier
	s_cbranch_scc0 .LBB0_2104
	v_cmp_gt_i32_e32 vcc, s51, v74
	v_lshl_add_u32 v78, v74, 2, 0
	s_and_saveexec_b64 s[20:21], vcc
	s_cbranch_execz .LBB0_2097
	s_mov_b32 s19, s11
	v_lshlrev_b32_e32 v4, 8, v74
	s_lshl_b64 s[22:23], s[18:19], 2
	s_add_u32 s54, s0, s22
	v_ashrrev_i32_e32 v5, 31, v4
	s_addc_u32 s55, s1, s23
	v_lshlrev_b64 v[4:5], 2, v[4:5]
	s_add_u32 s22, s2, s22
	v_lshl_add_u64 v[6:7], s[0:1], 0, v[4:5]
	v_lshl_add_u64 v[4:5], s[2:3], 0, v[4:5]
	s_addc_u32 s23, s3, s23
	global_load_dword v8, v3, s[54:55] offset:-4
	global_load_dword v10, v3, s[22:23] offset:-4
	global_load_dword v9, v[6:7], off offset:1020
	global_load_dword v11, v[4:5], off offset:1020
	v_lshl_add_u32 v4, s53, 3, v74
	v_ashrrev_i32_e32 v5, 31, v4
	v_lshl_add_u64 v[4:5], v[4:5], 2, s[6:7]
	global_load_dword v2, v[4:5], off
	s_waitcnt vmcnt(1)
	v_pk_add_f32 v[4:5], v[8:9], v[10:11]
	s_nop 0
	v_sub_f32_e32 v4, v4, v5
	s_waitcnt vmcnt(0)
	v_add_f32_e32 v2, v2, v4
	v_sub_f32_e32 v2, v2, v10
	v_mul_f32_e32 v2, 0x3fb8aa3b, v2
	v_exp_f32_e32 v2, v2
	ds_write_b32 v78, v2 offset:33024

; DI void mlstm_unit(const Args& a, LAS unsigned char* lds, int b, int h, int J) {
;     ...
;     for (int i = 0; i < 2; ++i) { const int idx = tid + 512 * i, rw = 64 * kt0 + (idx >> 4), ch = idx & 15; kreg[i] = *(const u32x4*)(KB + (size_t)rw * 512 + ch * 8); vreg[i] = *(const u32x4*)(VB + (size_t)rw * 512 + ch * 8); }
;     if (tid < 64) breg = BETA[64 * kt0 + tid];
.LBB0_2106:
	s_lshl_b32 s17, s53, 11
	s_lshl_b32 s2, s10, 10
	s_add_u32 s0, s24, s2
	s_addc_u32 s1, s25, 0
	s_add_u32 s0, s0, s16
	s_addc_u32 s1, s1, 0
	s_add_u32 s2, s30, s2
	s_addc_u32 s3, s31, 0
	v_ashrrev_i32_e32 v69, 4, v74
	s_add_u32 s2, s2, s16
	v_lshlrev_b32_e32 v2, 4, v74
	v_add_u32_e32 v70, s18, v69
	s_addc_u32 s3, s3, 0
	v_and_b32_e32 v2, 0xf0, v2
	v_ashrrev_i32_e32 v71, 31, v70
	v_lshl_add_u64 v[72:73], s[2:3], 0, v[2:3]
	v_lshl_add_u64 v[78:79], s[0:1], 0, v[2:3]
	v_lshlrev_b64 v[70:71], 10, v[70:71]
	v_lshl_add_u64 v[80:81], v[72:73], 0, v[70:71]
	v_lshl_add_u64 v[70:71], v[78:79], 0, v[70:71]
	v_add_u32_e32 v2, 0x200, v74
	s_waitcnt vmcnt(0)
	v_mov_b64_e32 v[132:133], v[200:201]
	v_mov_b64_e32 v[134:135], v[202:203]
	v_mov_b64_e32 v[136:137], v[204:205]
	v_mov_b64_e32 v[138:139], v[206:207]
	v_ashrrev_i32_e32 v70, 4, v2
	v_add_u32_e32 v80, s18, v70
	v_ashrrev_i32_e32 v81, 31, v80
	v_lshlrev_b64 v[80:81], 10, v[80:81]
	v_lshl_add_u64 v[72:73], v[72:73], 0, v[80:81]
	v_lshl_add_u64 v[78:79], v[78:79], 0, v[80:81]
	v_mov_b64_e32 v[140:141], v[208:209]
	v_mov_b64_e32 v[142:143], v[210:211]
	v_mov_b64_e32 v[144:145], v[212:213]
	v_mov_b64_e32 v[146:147], v[214:215]
	s_lshl_b32 s0, s17, 2
	s_add_u32 s0, s33, s0
	s_addc_u32 s1, s34, 0
	v_cmp_gt_i32_e64 s[2:3], 64, v74
	v_mov_b32_e32 v168, 0
	s_and_saveexec_b64 s[20:21], s[2:3]
	s_cbranch_execz .LBB0_2108
	v_add_u32_e32 v72, s18, v74
	v_ashrrev_i32_e32 v73, 31, v72
	v_lshl_add_u64 v[72:73], v[72:73], 2, s[0:1]
	global_load_dword v168, v[72:73], off
